# w_out/w_down transposes moved from P1 critical path into P5 idle workgroups (bx>=130)
# speedup vs baseline: 1.0155x; 1.0155x over previous
; __device__ __forceinline__ unsigned pk2(float lo, float hi) { f32x2_t v = {lo, hi}; bf16x2_t b = __builtin_convertvector(v, bf16x2_t); return __builtin_bit_cast(unsigned, b); }
; #define REP(k) for (int rep_ = 0; rep_ < (((DUPMASK) >> (k)) & 1 ? 2 : 1); ++rep_)
; #define A (*args_opaque((CArgs*)__builtin_amdgcn_kernarg_segment_ptr()))
; #define PHASE_IDS() const int wave = wave_s; int tid = lane_id_asm() + 64 * wave_s; asm volatile("" : "+v"(tid)); const int lane = tid & 63; (void)lane; (void)wave
; __device__ __forceinline__ void p1_tables(ArgsRef A, int tid, int first_block) {
;     ...
;         for (int u = 0; u < 4; ++u) { const int i = i0 + u * NGT; if (i < 32 * 8 * 32 * 64) { const int im = ((16 * ((i >> 11) & 7) + (i & 15)) >> 6) & 1; float v[8];
; #pragma unroll
;             for (int k = 0; k < 8; ++k) { const float br = bb4[u][k >> 1][2 * (k & 1)], bi = bb4[u][k >> 1][2 * (k & 1) + 1]; v[k] = im ? (pr4[u] * bi + pi4[u] * br) : (pr4[u] * br - pi4[u] * bi); }
;             u32x4 o; o.x = pk2(v[0], v[1]); o.y = pk2(v[2], v[3]); o.z = pk2(v[4], v[5]); o.w = pk2(v[6], v[7]);
;             *(u32x4*)(ET + (size_t)i * 8) = o; } } } }
; __global__ void __launch_bounds__(512, 2) fwd_kernel(Args A0) {
;     ...
;     REP(1) {if (bx >= 69) { PHASE_IDS(); p1_tables(A, tid, 69); __syncthreads(); idle_transposes(A, lds, lane, wave, 69, 0); __syncthreads(); }
.LBB0_195:
	v_mov_b32_e32 v50, v21
	v_mov_b32_e32 v51, v22
	v_mov_b32_e32 v48, v20
	v_mov_b32_e32 v49, v23
	v_pk_mul_f32 v[50:51], v[76:77], v[50:51] op_sel:[1,0] op_sel_hi:[0,1]
	v_mov_b32_e32 v52, v21
	v_mov_b32_e32 v53, v23
	v_and_b32_e32 v54, 0x2000, v70
	v_pk_fma_f32 v[48:49], v[76:77], v[48:49], v[50:51]
	v_mov_b32_e32 v50, v20
	v_mov_b32_e32 v51, v22
	v_pk_mul_f32 v[52:53], v[76:77], v[52:53] op_sel_hi:[0,1]
	v_pk_fma_f32 v[50:51], v[76:77], v[50:51], v[52:53] op_sel:[1,0,0] neg_lo:[0,0,1] neg_hi:[0,0,1]
	v_cmp_eq_u32_e32 vcc, 0, v54
	v_mov_b32_e32 v52, v13
	v_mov_b32_e32 v53, v15
	v_cndmask_b32_e32 v54, v49, v51, vcc
	v_cndmask_b32_e32 v55, v48, v50, vcc
	v_mov_b32_e32 v50, v13
	v_mov_b32_e32 v51, v14
	v_mov_b32_e32 v48, v12
	v_mov_b32_e32 v49, v15
	v_pk_mul_f32 v[50:51], v[76:77], v[50:51] op_sel:[1,0] op_sel_hi:[0,1]
	v_pk_fma_f32 v[48:49], v[76:77], v[48:49], v[50:51]
	v_mov_b32_e32 v50, v12
	v_mov_b32_e32 v51, v14
	v_pk_mul_f32 v[52:53], v[76:77], v[52:53] op_sel_hi:[0,1]
	v_pk_fma_f32 v[50:51], v[76:77], v[50:51], v[52:53] op_sel:[1,0,0] neg_lo:[0,0,1] neg_hi:[0,0,1]
	v_mov_b32_e32 v52, v5
	v_cndmask_b32_e32 v56, v49, v51, vcc
	v_cndmask_b32_e32 v57, v48, v50, vcc
	v_mov_b32_e32 v50, v5
	v_mov_b32_e32 v51, v6
	v_mov_b32_e32 v48, v4
	v_mov_b32_e32 v49, v7
	v_pk_mul_f32 v[50:51], v[76:77], v[50:51] op_sel:[1,0] op_sel_hi:[0,1]
	v_mov_b32_e32 v53, v7
	v_pk_fma_f32 v[48:49], v[76:77], v[48:49], v[50:51]
	v_mov_b32_e32 v50, v4
	v_mov_b32_e32 v51, v6
	v_pk_mul_f32 v[52:53], v[76:77], v[52:53] op_sel_hi:[0,1]
	v_pk_fma_f32 v[50:51], v[76:77], v[50:51], v[52:53] op_sel:[1,0,0] neg_lo:[0,0,1] neg_hi:[0,0,1]
	v_mov_b32_e32 v52, v1
	v_cndmask_b32_e32 v58, v49, v51, vcc
	v_cndmask_b32_e32 v59, v48, v50, vcc
	v_mov_b32_e32 v50, v1
	v_mov_b32_e32 v51, v2
	v_mov_b32_e32 v48, v0
	v_mov_b32_e32 v49, v3
	v_pk_mul_f32 v[50:51], v[76:77], v[50:51] op_sel:[1,0] op_sel_hi:[0,1]
	v_mov_b32_e32 v53, v3
	v_pk_fma_f32 v[48:49], v[76:77], v[48:49], v[50:51]
	v_mov_b32_e32 v50, v0
	v_mov_b32_e32 v51, v2
	v_pk_mul_f32 v[52:53], v[76:77], v[52:53] op_sel_hi:[0,1]
	v_pk_fma_f32 v[50:51], v[76:77], v[50:51], v[52:53] op_sel:[1,0,0] neg_lo:[0,0,1] neg_hi:[0,0,1]
	v_ashrrev_i32_e32 v71, 31, v70
	v_cndmask_b32_e32 v51, v49, v51, vcc
	v_cndmask_b32_e32 v52, v48, v50, vcc
	v_cvt_pk_bf16_f32 v48, v55, v54
	v_cvt_pk_bf16_f32 v49, v57, v56
	v_cvt_pk_bf16_f32 v50, v59, v58
	v_cvt_pk_bf16_f32 v51, v52, v51
	v_lshl_add_u64 v[52:53], v[70:71], 4, s[26:27]
	global_store_dwordx4 v[52:53], v[48:51], off
	s_branch .LBB0_183
.LBB0_196:
	s_or_b64 exec, exec, s[20:21]
	s_waitcnt lgkmcnt(0)
	s_barrier
.LBB0_207:
	s_barrier

; #define LAS __attribute__((address_space(3)))
; #define A (*args_opaque((CArgs*)__builtin_amdgcn_kernarg_segment_ptr()))
; __device__ __forceinline__ void idle_transposes(ArgsRef A, LAS unsigned char* lds, int lane, int wave, int first_block, int which) {
;     unsigned char* ws = A.ws; const int gw = ((int)blockIdx.x - first_block) * 8 + wave, NGW = ((int)gridDim.x - first_block) * 8;
;     LAS float* scr = (LAS float*)(lds + wave * 16384);
;     constexpr int I4 = 16 * 32, I5 = 16 * 176, I6 = 44 * 32;
;     if (which == 0) {
;         for (int it = gw; it < I4 + I6; it += NGW) {
;             if (it < I4) tr_item(A.in[25], 1024, 1024, (bf16_t*)(ws + WS_WOUT), scr, it, lane, 0, nullptr);
;             else tr_item(A.in[30], 2816, 1024, (bf16_t*)(ws + WS_WDN), scr, it - I4, lane, 0, nullptr);
;         }
.Ltrx_entry:
	v_writelane_b32 v120, s3, 0
	v_writelane_b32 v120, s20, 1
	v_writelane_b32 v120, s21, 2
	v_writelane_b32 v120, s30, 3
	v_writelane_b32 v120, s31, 4
	v_writelane_b32 v120, s33, 5
	v_writelane_b32 v120, s34, 6
	v_writelane_b32 v120, s35, 7
	v_writelane_b32 v120, s36, 8
	v_writelane_b32 v120, s37, 9
	v_writelane_b32 v120, s38, 10
	v_mov_b32_e32 v121, v3
	v_readlane_b32 s72, v254, 60
	v_mbcnt_lo_u32_b32 v142, -1, 0
	v_mbcnt_hi_u32_b32 v142, -1, v142
	v_add_u32_e32 v142, s81, v142
	s_lshr_b32 s1, s81, 6
	s_lshl_b32 s4, s2, 3
	s_add_i32 s1, s1, s4
	s_add_i32 s1, s1, 0xfffffbf0
	s_cmpk_gt_i32 s1, 0x77f
	s_mov_b64 s[20:21], s[92:93]
	s_waitcnt lgkmcnt(0)
	s_barrier
	s_cbranch_scc1 .Ltrx_done
	s_load_dwordx2 s[24:25], s[20:21], 0xc8
	s_load_dwordx2 s[4:5], s[20:21], 0xf0
	s_nop 0
	s_load_dwordx2 s[20:21], s[20:21], 0x100
	v_lshlrev_b32_e32 v1, 2, v142
	v_and_b32_e32 v2, 0x7c, v1
	v_lshlrev_b32_e32 v1, 3, v142
	v_mov_b32_e32 v3, 0
	v_and_b32_e32 v1, 56, v1
	v_lshlrev_b32_e32 v8, 1, v1
	v_mov_b32_e32 v9, v3
	v_bfe_u32 v17, v142, 3, 3
	s_waitcnt lgkmcnt(0)
	v_lshl_add_u64 v[12:13], s[20:21], 0, v[8:9]
	s_mov_b64 s[20:21], 0x1240000
	v_bfe_u32 v0, v142, 5, 1
	v_mul_u32_u24_e32 v7, 0x84, v1
	v_lshl_add_u64 v[8:9], v[12:13], 0, s[20:21]
	v_lshlrev_b32_e32 v1, 2, v17
	s_mov_b64 s[20:21], 0x540000
	s_lshl_b32 s3, s50, 3
	s_add_i32 s3, s3, 0xfffffbf0
	v_lshl_add_u64 v[4:5], s[4:5], 0, v[2:3]
	v_add_u32_e32 v6, s72, v2
	s_movk_i32 s4, 0x84
	v_add3_u32 v18, s72, v7, v1
	v_or_b32_e32 v19, 8, v17
	v_or_b32_e32 v20, 16, v17
	v_or_b32_e32 v21, 24, v17
	v_lshl_add_u64 v[10:11], s[24:25], 0, v[2:3]
	v_lshl_add_u64 v[12:13], v[12:13], 0, s[20:21]
	v_mov_b32_e32 v1, v0
	s_mov_b32 s21, 0
	s_branch .Ltrx_199

; #define LAS __attribute__((address_space(3)))
; #define A (*args_opaque((CArgs*)__builtin_amdgcn_kernarg_segment_ptr()))
; __device__ __forceinline__ void idle_transposes(ArgsRef A, LAS unsigned char* lds, int lane, int wave, int first_block, int which) {
;     unsigned char* ws = A.ws; const int gw = ((int)blockIdx.x - first_block) * 8 + wave, NGW = ((int)gridDim.x - first_block) * 8;
;     LAS float* scr = (LAS float*)(lds + wave * 16384);
;     constexpr int I4 = 16 * 32, I5 = 16 * 176, I6 = 44 * 32;
;     if (which == 0) {
;         for (int it = gw; it < I4 + I6; it += NGW) {
;             if (it < I4) tr_item(A.in[25], 1024, 1024, (bf16_t*)(ws + WS_WOUT), scr, it, lane, 0, nullptr);
;             else tr_item(A.in[30], 2816, 1024, (bf16_t*)(ws + WS_WDN), scr, it - I4, lane, 0, nullptr);
;         }
.Ltrx_done:
	s_waitcnt lgkmcnt(0)
	s_barrier
	v_readlane_b32 s3, v120, 0
	v_readlane_b32 s20, v120, 1
	v_readlane_b32 s21, v120, 2
	v_readlane_b32 s30, v120, 3
	v_readlane_b32 s31, v120, 4
	v_readlane_b32 s33, v120, 5
	v_readlane_b32 s34, v120, 6
	v_readlane_b32 s35, v120, 7
	v_readlane_b32 s36, v120, 8
	v_readlane_b32 s37, v120, 9
	v_readlane_b32 s38, v120, 10
	v_mov_b32_e32 v3, v121
	s_nop 3
